# scan loops: packed f32 multiplies split into scalar ops (on top of unpacked attention adds)
# baseline (speedup 1.0000x reference)
; DI unsigned pack2(float lo, float hi) { const f32x2 v = (f32x2){lo, hi}; return __builtin_bit_cast(unsigned, __builtin_convertvector(v, bf16x2_t)); }
; DI void hgrn_scan_mfma(const Params& p, char* shm) {
;     ...
;             { const bf16_t* kt16 = (const bf16_t*)KtL; const bf16_t* v16 = (const bf16_t*)VL; const int vcol = w * 16 + l15;
;     ...
;               const bf16x8 vf = __builtin_bit_cast(bf16x8, (u32x4){HG_U2(v16, g * 4 + 0, g * 4 + 1, vcol), HG_U2(v16, g * 4 + 2, g * 4 + 3, vcol), HG_U2(v16, 16 + g * 4 + 0, 16 + g * 4 + 1, vcol), HG_U2(v16, 16 + g * 4 + 2, 16 + g * 4 + 3, vcol)});
;               f32x4 sc00 = (f32x4){0.f, 0.f, 0.f, 0.f}, sc01 = sc00, sc11 = sc00, o0 = sc00, o1 = sc00;
; #pragma unroll
;               for (int kc = 0; kc < 4; ++kc) {
;                   const bf16x8 aK0 = *(const bf16x8*)(KtL + l15 * QS + kc * 64 + g * 16), aK1 = *(const bf16x8*)(KtL + (16 + l15) * QS + kc * 64 + g * 16);
;                   const bf16x8 bQ0 = *(const bf16x8*)(QtL + l15 * QS + kc * 64 + g * 16), bQ1 = *(const bf16x8*)(QtL + (16 + l15) * QS + kc * 64 + g * 16);
;                   sc00 = __builtin_amdgcn_mfma_f32_16x16x32_bf16(aK0, bQ0, sc00, 0, 0, 0);
;                   sc01 = __builtin_amdgcn_mfma_f32_16x16x32_bf16(aK0, bQ1, sc01, 0, 0, 0);
;                   sc11 = __builtin_amdgcn_mfma_f32_16x16x32_bf16(aK1, bQ1, sc11, 0, 0, 0);
;                   const int kp = kc;
;                   const u32x2 qa0 = *(const u32x2*)(QtL + l15 * QS + ((2 * kp) * 16 + g * 4) * 2), qb0 = *(const u32x2*)(QtL + l15 * QS + ((2 * kp + 1) * 16 + g * 4) * 2);
;                   const u32x2 qa1 = *(const u32x2*)(QtL + (16 + l15) * QS + ((2 * kp) * 16 + g * 4) * 2), qb1 = *(const u32x2*)(QtL + (16 + l15) * QS + ((2 * kp + 1) * 16 + g * 4) * 2);
;                   const bf16x8 sw = __builtin_bit_cast(bf16x8, (u32x4){pack2(S[2 * kp][0], S[2 * kp][1]), pack2(S[2 * kp][2], S[2 * kp][3]), pack2(S[2 * kp + 1][0], S[2 * kp + 1][1]), pack2(S[2 * kp + 1][2], S[2 * kp + 1][3])});
;                   o0 = __builtin_amdgcn_mfma_f32_16x16x32_bf16(__builtin_bit_cast(bf16x8, (u32x4){qa0.x, qa0.y, qb0.x, qb0.y}), sw, o0, 0, 0, 0);
;                   o1 = __builtin_amdgcn_mfma_f32_16x16x32_bf16(__builtin_bit_cast(bf16x8, (u32x4){qa1.x, qa1.y, qb1.x, qb1.y}), sw, o1, 0, 0, 0); }
; #pragma unroll
;               for (int r = 0; r < 4; ++r) if (g * 4 + r > l15) { sc00[r] = 0.f; sc11[r] = 0.f; }
.LBB0_2441:
	v_mul_f32_e32 v58, v98, v58
	v_mul_f32_e32 v59, v99, v59
	v_mul_f32_e32 v56, v96, v56
	v_mul_f32_e32 v57, v97, v57
	ds_read_b128 v[96:99], v160 offset:50176
	v_mul_f32_e32 v62, v94, v62
	v_mul_f32_e32 v63, v95, v63
	v_mul_f32_e32 v60, v92, v60
	v_mul_f32_e32 v61, v93, v61
	ds_read_b128 v[68:71], v160 offset:54528
	ds_read_b128 v[92:95], v160 offset:32768
	v_mul_f32_e32 v46, v110, v46
	v_mul_f32_e32 v47, v111, v47
	v_mul_f32_e32 v44, v108, v44
	v_mul_f32_e32 v45, v109, v45
	v_mul_f32_e32 v50, v106, v50
	v_mul_f32_e32 v51, v107, v51
	v_mul_f32_e32 v48, v104, v48
	v_mul_f32_e32 v49, v105, v49
	v_mul_f32_e32 v54, v102, v54
	v_mul_f32_e32 v55, v103, v55
	v_mul_f32_e32 v52, v100, v52
	v_mul_f32_e32 v53, v101, v53
	ds_read_b128 v[100:103], v160 offset:37120
	ds_read_b128 v[104:107], v160 offset:50240
	ds_read_b128 v[108:111], v160 offset:32832
	ds_read_b128 v[162:165], v160 offset:54592
	ds_read_b128 v[166:169], v160 offset:37184
	v_mul_f32_e32 v66, v90, v66
	v_mul_f32_e32 v67, v91, v67
	s_waitcnt lgkmcnt(5)
	v_mfma_f32_16x16x32_bf16 v[90:93], v[96:99], v[92:95], 0
	v_mul_f32_e64 v64, v88, v64
	v_mul_f32_e64 v65, v89, v65
	v_mul_f32_e32 v78, v74, v78
	v_mul_f32_e32 v79, v75, v79
	v_mul_f32_e32 v76, v72, v76
	v_mul_f32_e32 v77, v73, v77
	s_waitcnt lgkmcnt(4)
	v_mfma_f32_16x16x32_bf16 v[170:173], v[68:71], v[100:103], 0
	v_mul_f32_e64 v70, v86, v82
	v_mul_f32_e64 v71, v87, v83
	v_mul_f32_e32 v68, v84, v80
	v_mul_f32_e32 v69, v85, v81
	ds_read_b128 v[84:87], v160 offset:50304
	s_waitcnt lgkmcnt(3)
	v_mfma_f32_16x16x32_bf16 v[80:83], v[104:107], v[108:111], v[90:93]
	s_nop 2
	ds_read_b128 v[88:91], v160 offset:54656
	ds_read_b128 v[92:95], v160 offset:32896
	v_cvt_pk_bf16_f32 v186, v52, v53
	v_cvt_pk_bf16_f32 v187, v54, v55
	s_waitcnt lgkmcnt(3)
	v_mfma_f32_16x16x32_bf16 v[108:111], v[162:165], v[166:169], v[170:173]
	ds_read_b128 v[162:165], v160 offset:37248
	s_nop 1
	ds_read_b128 v[170:173], v160 offset:50368
	ds_read_b128 v[174:177], v160 offset:32960
	ds_read_b128 v[72:75], v160 offset:54720
	ds_read_b128 v[178:181], v160 offset:37312
	v_cvt_pk_bf16_f32 v188, v56, v57
	s_waitcnt lgkmcnt(4)
	v_mfma_f32_16x16x32_bf16 v[88:91], v[88:91], v[162:165], v[108:111]
	v_cvt_pk_bf16_f32 v189, v58, v59
	s_add_i32 s14, s74, 32
	s_and_b64 s[0:1], s[12:13], exec
	v_mfma_f32_16x16x32_bf16 v[92:95], v[84:87], v[92:95], v[80:83]
	ds_read_b64 v[80:81], v198 offset:31104
	ds_read_b64 v[82:83], v198 offset:31136
	ds_read2_b64 v[108:111], v195 offset1:4
	s_waitcnt lgkmcnt(3)
	v_mfma_f32_16x16x32_bf16 v[72:75], v[72:75], v[178:181], v[88:91]
	v_mov_b32_e32 v0, s39
	ds_read2_b64 v[88:91], v197 offset0:32 offset1:36
	v_mfma_f32_16x16x32_bf16 v[96:99], v[96:99], v[100:103], 0
	s_cselect_b32 s0, s14, s77
	s_add_u32 s0, s50, s0
	v_mfma_f32_16x16x32_bf16 v[92:95], v[170:173], v[174:177], v[92:95]
	v_cvt_pk_bf16_f32 v174, v44, v45
	v_cvt_pk_bf16_f32 v175, v46, v47
	v_cvt_pk_bf16_f32 v176, v48, v49
	v_cvt_pk_bf16_f32 v177, v50, v51
	v_mfma_f32_16x16x32_bf16 v[96:99], v[104:107], v[166:169], v[96:99]
	s_nop 2
	v_cndmask_b32_e64 v0, v92, v0, s[4:5]
	v_cndmask_b32_e64 v0, v0, v92, s[6:7]
	v_cndmask_b32_e64 v3, v94, 0, s[8:9]
	s_waitcnt lgkmcnt(1)
	v_mfma_f32_16x16x32_bf16 v[100:103], v[108:111], v[174:177], 0
	ds_read2_b64 v[108:111], v195 offset0:8 offset1:12
	ds_read2_b64 v[182:185], v197 offset0:40 offset1:44
	ds_read2_b64 v[104:107], v195 offset0:16 offset1:20
	ds_read2_b64 v[166:169], v197 offset0:48 offset1:52
	s_addc_u32 s1, s51, 0
	s_waitcnt lgkmcnt(4)
	v_mfma_f32_16x16x32_bf16 v[88:91], v[88:91], v[174:177], 0
	v_cvt_pk_bf16_f32 v174, v60, v61
	v_cvt_pk_bf16_f32 v175, v62, v63
	v_cvt_pk_bf16_f32 v176, v64, v65
	s_waitcnt lgkmcnt(3)
	v_mfma_f32_16x16x32_bf16 v[100:103], v[108:111], v[186:189], v[100:103]
	v_cvt_pk_bf16_f32 v177, v66, v67
	s_lshl_b64 s[0:1], s[0:1], 11
	v_mfma_f32_16x16x32_bf16 v[84:87], v[84:87], v[162:165], v[96:99]
	s_sub_i32 s38, s38, 64
	s_add_i32 s74, s74, 64
	s_and_b64 vcc, exec, s[54:55]
	s_waitcnt lgkmcnt(2)
	v_mfma_f32_16x16x32_bf16 v[88:91], v[182:185], v[186:189], v[88:91]
	ds_read2_b64 v[108:111], v195 offset0:24 offset1:28
	ds_read2_b64 v[182:185], v197 offset0:56 offset1:60
	v_cvt_pk_bf16_f32 v186, v68, v69
	v_cvt_pk_bf16_f32 v187, v70, v71
	s_waitcnt lgkmcnt(3)
	v_mfma_f32_16x16x32_bf16 v[96:99], v[104:107], v[174:177], v[100:103]
	v_cvt_pk_bf16_f32 v188, v76, v77
	v_cvt_pk_bf16_f32 v189, v78, v79
	s_nop 0
	v_mov_b32_e32 v100, s39
	v_mfma_f32_16x16x32_bf16 v[84:87], v[170:173], v[178:181], v[84:87]
	v_cndmask_b32_e64 v1, v72, v100, s[4:5]
	v_cndmask_b32_e64 v100, v1, v72, s[6:7]
	v_cndmask_b32_e64 v1, 0, v93, s[6:7]
	s_waitcnt lgkmcnt(2)
; DI unsigned pack2(float lo, float hi) { const f32x2 v = (f32x2){lo, hi}; return __builtin_bit_cast(unsigned, __builtin_convertvector(v, bf16x2_t)); }
; DI void hgrn_scan_mfma(const Params& p, char* shm) {
;     ...
;               o0 = __builtin_amdgcn_mfma_f32_16x16x32_bf16(__builtin_bit_cast(bf16x8, (u32x4){pack2(sc00[0], sc00[1]), pack2(sc00[2], sc00[3]), 0u, 0u}), vf, o0, 0, 0, 0);
;               o1 = __builtin_amdgcn_mfma_f32_16x16x32_bf16(__builtin_bit_cast(bf16x8, (u32x4){pack2(sc01[0], sc01[1]), pack2(sc01[2], sc01[3]), pack2(sc11[0], sc11[1]), pack2(sc11[2], sc11[3])}), vf, o1, 0, 0, 0);
; #pragma unroll
;               for (int r = 0; r < 4; ++r) {
;                   const long rb_ = (long)HG_ROW(b, dir, ch * C), st_ = dir ? -(long)D : (long)D; bf16_t* op_ = Oo + rb_ * D + head * 128 + vcol + (long)(g * 4 + r) * st_;
;                   op_[0] = (bf16_t)(pack2(o0[r], 0.f) & 0xffffu); op_[16 * st_] = (bf16_t)(pack2(o1[r], 0.f) & 0xffffu); }
; #pragma unroll
;               for (int kt = 0; kt < 8; ++kt) { const f32x4 dcy = *(const f32x4*)(eBL + kt * 16 + g * 4); const int kcol = kt * 16 + l15;
;                   const bf16x8 kl = __builtin_bit_cast(bf16x8, (u32x4){HG_U2(kt16, g * 4 + 0, g * 4 + 1, kcol), HG_U2(kt16, g * 4 + 2, g * 4 + 3, kcol), HG_U2(kt16, 16 + g * 4 + 0, 16 + g * 4 + 1, kcol), HG_U2(kt16, 16 + g * 4 + 2, 16 + g * 4 + 3, kcol)});
;                   S[kt] = __builtin_amdgcn_mfma_f32_16x16x32_bf16(kl, vf, S[kt], 0, 0, 0) * dcy; }
	v_mfma_f32_16x16x32_bf16 v[88:91], v[166:169], v[174:177], v[88:91]
	v_cndmask_b32_e64 v72, v95, 0, s[10:11]
	v_cvt_pk_bf16_f32 v0, v0, v1
	v_cvt_pk_bf16_f32 v1, v3, v72
	s_waitcnt lgkmcnt(1)
	v_mfma_f32_16x16x32_bf16 v[92:95], v[108:111], v[186:189], v[96:99]
	v_mov_b32_e32 v3, v2
	v_cvt_pk_bf16_f32 v84, v84, v85
	v_cvt_pk_bf16_f32 v85, v86, v87
	v_cndmask_b32_e64 v96, 0, v73, s[6:7]
	v_cndmask_b32_e64 v97, v74, 0, s[8:9]
	v_cndmask_b32_e64 v98, v75, 0, s[10:11]
	v_cvt_pk_bf16_f32 v86, v100, v96
	v_cvt_pk_bf16_f32 v87, v97, v98
	s_waitcnt lgkmcnt(0)
	v_mfma_f32_16x16x32_bf16 v[88:91], v[182:185], v[186:189], v[88:91]
	v_mfma_f32_16x16x32_bf16 v[72:75], v[0:3], v[80:83], v[92:95]
	v_lshl_add_u64 v[0:1], v[132:133], 0, s[0:1]
	v_mfma_f32_16x16x32_bf16 v[84:87], v[84:87], v[80:83], v[88:91]
	s_nop 4
	v_lshl_add_u64 v[88:89], v[134:135], 1, v[0:1]
	v_cvt_pk_bf16_f32 v3, v72, s0
	global_store_short v[88:89], v3, off
	v_cvt_pk_bf16_f32 v3, v84, s0
	v_lshl_add_u64 v[88:89], v[88:89], 0, s[52:53]
	global_store_short v[88:89], v3, off
	v_lshl_add_u64 v[88:89], v[136:137], 1, v[0:1]
	v_cvt_pk_bf16_f32 v3, v73, s0
	global_store_short v[88:89], v3, off
	v_cvt_pk_bf16_f32 v3, v85, s0
	v_lshl_add_u64 v[72:73], v[88:89], 0, s[52:53]
	global_store_short v[72:73], v3, off
	v_lshl_add_u64 v[72:73], v[138:139], 1, v[0:1]
	v_cvt_pk_bf16_f32 v3, v74, s0
	global_store_short v[72:73], v3, off
	v_cvt_pk_bf16_f32 v3, v86, s0
	v_lshl_add_u64 v[72:73], v[72:73], 0, s[52:53]
	global_store_short v[72:73], v3, off
	v_lshl_add_u64 v[0:1], v[140:141], 1, v[0:1]
	v_cvt_pk_bf16_f32 v3, v75, s0
	global_store_short v[0:1], v3, off
	v_cvt_pk_bf16_f32 v3, v87, s0
	v_lshl_add_u64 v[0:1], v[0:1], 0, s[52:53]
	global_store_short v[0:1], v3, off
	ds_read_b128 v[72:75], v149 offset:58880
	ds_read_b64 v[200:201], v199 offset:20736
	ds_read_b64 v[202:203], v199 offset:20768
	ds_read_b64 v[204:205], v199 offset:22032
	ds_read_b64 v[206:207], v199 offset:22064
	ds_read_b64 v[208:209], v199 offset:23328
	ds_read_b64 v[210:211], v199 offset:23360
	ds_read_b64 v[212:213], v199 offset:24624
	ds_read_b64 v[214:215], v199 offset:24656
	ds_read_b64 v[216:217], v199 offset:25920
	ds_read_b64 v[218:219], v199 offset:25952
	ds_read_b64 v[220:221], v199 offset:27216
	ds_read_b64 v[222:223], v199 offset:27248
	ds_read_b64 v[224:225], v199 offset:28512
	ds_read_b64 v[226:227], v199 offset:28544
	ds_read_b64 v[228:229], v199 offset:29808
	ds_read_b64 v[230:231], v199 offset:29840
	s_waitcnt lgkmcnt(14)
	v_mfma_f32_16x16x32_bf16 v[44:47], v[200:203], v[80:83], v[44:47]
	ds_read_b128 v[84:87], v149 offset:58944
	s_waitcnt lgkmcnt(13)
	v_mfma_f32_16x16x32_bf16 v[48:51], v[204:207], v[80:83], v[48:51]
	s_nop 4
	v_mul_f32_e32 v46, v74, v46
	v_mul_f32_e32 v47, v75, v47
	v_mul_f32_e32 v44, v72, v44
	v_mul_f32_e32 v45, v73, v45
	ds_read_b128 v[72:75], v149 offset:59008
	s_waitcnt lgkmcnt(1)
	v_mul_f32_e32 v50, v86, v50
	v_mul_f32_e32 v51, v87, v51
	v_mul_f32_e32 v48, v84, v48
	v_mul_f32_e32 v49, v85, v49
	v_mfma_f32_16x16x32_bf16 v[52:55], v[208:211], v[80:83], v[52:55]
	ds_read_b128 v[84:87], v149 offset:59072
	v_mfma_f32_16x16x32_bf16 v[56:59], v[212:215], v[80:83], v[56:59]
	s_nop 4
	s_waitcnt lgkmcnt(1)
	v_mul_f32_e32 v54, v74, v54
	v_mul_f32_e32 v55, v75, v55
	v_mul_f32_e32 v52, v72, v52
	v_mul_f32_e32 v53, v73, v53
	ds_read_b128 v[72:75], v149 offset:59136
	s_waitcnt lgkmcnt(1)
	v_mul_f32_e32 v58, v86, v58
	v_mul_f32_e32 v59, v87, v59
	v_mul_f32_e32 v56, v84, v56
	v_mul_f32_e32 v57, v85, v57
	v_mfma_f32_16x16x32_bf16 v[60:63], v[216:219], v[80:83], v[60:63]
	ds_read_b128 v[84:87], v149 offset:59200
	v_mfma_f32_16x16x32_bf16 v[64:67], v[220:223], v[80:83], v[64:67]
	s_nop 4
	s_waitcnt lgkmcnt(1)
	v_mul_f32_e32 v62, v74, v62
	v_mul_f32_e32 v63, v75, v63
	v_mul_f32_e32 v60, v72, v60
	v_mul_f32_e32 v61, v73, v61
	ds_read_b128 v[72:75], v149 offset:59264
	s_waitcnt lgkmcnt(1)
	v_mul_f32_e32 v66, v86, v66
	v_mul_f32_e32 v67, v87, v67
	v_mul_f32_e32 v64, v84, v64
	v_mul_f32_e32 v65, v85, v65
	v_mfma_f32_16x16x32_bf16 v[68:71], v[224:227], v[80:83], v[68:71]
	ds_read_b128 v[84:87], v149 offset:59328
	s_nop 5
	s_waitcnt lgkmcnt(1)
	v_mul_f32_e32 v74, v74, v70
	v_mul_f32_e32 v75, v75, v71
	v_mul_f32_e32 v72, v72, v68
	v_mul_f32_e32 v73, v73, v69
	v_mfma_f32_16x16x32_bf16 v[68:71], v[228:231], v[80:83], v[76:79]
	s_nop 6
	s_waitcnt lgkmcnt(0)
	v_mul_f32_e32 v70, v86, v70
	v_mul_f32_e32 v71, v87, v71
	v_mul_f32_e32 v68, v84, v68
	v_mul_f32_e32 v69, v85, v69
	s_cbranch_vccnz .LBB0_2411
	s_mov_b32 s76, s75
	s_branch .LBB0_2417

.Lscanh_loop:
	s_waitcnt vmcnt(8)
	v_lshlrev_b32_e32 v80, 16, v12
	v_and_b32_e32 v81, 0xffff0000, v12
	v_lshlrev_b32_e32 v82, 16, v16
	v_and_b32_e32 v83, 0xffff0000, v16
	v_lshlrev_b32_e32 v84, 16, v13
	v_and_b32_e32 v85, 0xffff0000, v13
	v_lshlrev_b32_e32 v86, 16, v17
	v_and_b32_e32 v87, 0xffff0000, v17
	v_mul_f32_e32 v80, v80, v82
	v_mul_f32_e32 v81, v81, v83
	v_mul_f32_e32 v84, v84, v86
	v_mul_f32_e32 v85, v85, v87
	v_cvt_pk_bf16_f32 v76, v80, v81
	v_cvt_pk_bf16_f32 v77, v84, v85
	v_lshlrev_b32_e32 v80, 16, v14
	v_and_b32_e32 v81, 0xffff0000, v14
	v_lshlrev_b32_e32 v82, 16, v18
	v_and_b32_e32 v83, 0xffff0000, v18
	v_lshlrev_b32_e32 v84, 16, v15
	v_and_b32_e32 v85, 0xffff0000, v15
	v_lshlrev_b32_e32 v86, 16, v19
	v_and_b32_e32 v87, 0xffff0000, v19
	v_mul_f32_e32 v80, v80, v82
	v_mul_f32_e32 v81, v81, v83
	v_mul_f32_e32 v84, v84, v86
	v_mul_f32_e32 v85, v85, v87
	v_cvt_pk_bf16_f32 v78, v80, v81
	v_cvt_pk_bf16_f32 v79, v84, v85
	v_lshlrev_b32_e32 v80, 16, v196
	v_and_b32_e32 v81, 0xffff0000, v196
	v_lshlrev_b32_e32 v82, 16, v200
	v_and_b32_e32 v83, 0xffff0000, v200
	v_lshlrev_b32_e32 v84, 16, v197
	v_and_b32_e32 v85, 0xffff0000, v197
	v_lshlrev_b32_e32 v86, 16, v201
	v_and_b32_e32 v87, 0xffff0000, v201
	v_mul_f32_e32 v80, v80, v82
	v_mul_f32_e32 v81, v81, v83
	v_mul_f32_e32 v84, v84, v86
	v_mul_f32_e32 v85, v85, v87
	v_cvt_pk_bf16_f32 v246, v80, v81
	v_cvt_pk_bf16_f32 v247, v84, v85
	v_lshlrev_b32_e32 v80, 16, v198
	v_and_b32_e32 v81, 0xffff0000, v198
	v_lshlrev_b32_e32 v82, 16, v202
	v_and_b32_e32 v83, 0xffff0000, v202
	v_lshlrev_b32_e32 v84, 16, v199
	v_and_b32_e32 v85, 0xffff0000, v199
	v_lshlrev_b32_e32 v86, 16, v203
	v_and_b32_e32 v87, 0xffff0000, v203
	v_mul_f32_e32 v80, v80, v82
	v_mul_f32_e32 v81, v81, v83
	v_mul_f32_e32 v84, v84, v86
	v_mul_f32_e32 v85, v85, v87
	v_cvt_pk_bf16_f32 v248, v80, v81
	v_cvt_pk_bf16_f32 v249, v84, v85
	ds_write_b128 v158, v[76:79]
	ds_write_b128 v158, v[20:23] offset:8704
	ds_write_b128 v158, v[24:27] offset:17408
	ds_write_b128 v228, v[246:249]
	ds_write_b128 v228, v[204:207] offset:8704
	ds_write_b128 v228, v[208:211] offset:17408
	ds_write_b16 v230, v24 offset:0
	ds_write_b16_d16_hi v230, v24 offset:80
	ds_write_b16 v230, v25 offset:160
	ds_write_b16_d16_hi v230, v25 offset:240
	ds_write_b16 v230, v26 offset:320
	ds_write_b16_d16_hi v230, v26 offset:400
	ds_write_b16 v230, v27 offset:480
	ds_write_b16_d16_hi v230, v27 offset:560
	ds_write_b16 v230, v20 offset:10368
	ds_write_b16_d16_hi v230, v20 offset:10448
	ds_write_b16 v230, v21 offset:10528
	ds_write_b16_d16_hi v230, v21 offset:10608
	ds_write_b16 v230, v22 offset:10688
	ds_write_b16_d16_hi v230, v22 offset:10768
	ds_write_b16 v230, v23 offset:10848
	ds_write_b16_d16_hi v230, v23 offset:10928
	ds_write_b16 v231, v208 offset:0
	ds_write_b16_d16_hi v231, v208 offset:80
	ds_write_b16 v231, v209 offset:160
	ds_write_b16_d16_hi v231, v209 offset:240
	ds_write_b16 v231, v210 offset:320
	ds_write_b16_d16_hi v231, v210 offset:400
	ds_write_b16 v231, v211 offset:480
	ds_write_b16_d16_hi v231, v211 offset:560
	ds_write_b16 v231, v204 offset:10368
	ds_write_b16_d16_hi v231, v204 offset:10448
	ds_write_b16 v231, v205 offset:10528
	ds_write_b16_d16_hi v231, v205 offset:10608
	ds_write_b16 v231, v206 offset:10688
	ds_write_b16_d16_hi v231, v206 offset:10768
	ds_write_b16 v231, v207 offset:10848
	ds_write_b16_d16_hi v231, v207 offset:10928
	s_and_saveexec_b64 s[14:15], s[2:3]
	ds_write_b128 v229, v[4:7] offset:26112
	s_or_b64 exec, exec, s[14:15]
	s_add_i32 s75, s76, 2
	s_cmpk_lt_u32 s76, 0x46
	s_cselect_b64 s[56:57], -1, 0
	s_cmpk_gt_u32 s76, 0x45
	s_cselect_b64 s[54:55], -1, 0
	s_waitcnt lgkmcnt(0)
	s_barrier
	s_and_b64 vcc, exec, s[54:55]
	s_cbranch_vccnz .Lscanh_nopfa
	s_and_b64 vcc, exec, s[12:13]
	v_lshl_add_u32 v0, s75, 5, v113
	s_cbranch_vccnz .Lscanh_ia
	v_add3_u32 v1, v113, s74, 64
	v_cmp_lt_i32_e32 vcc, s47, v1
	s_and_saveexec_b64 s[14:15], vcc
	s_xor_b64 s[14:15], exec, s[14:15]
	v_add_u32_e32 v0, s38, v156
	v_add_u32_e32 v0, 0x9df, v0
	s_andn2_saveexec_b64 s[14:15], s[14:15]
	v_sub_u32_e32 v0, 0xff, v0
	s_or_b64 exec, exec, s[14:15]

.Lscanh_steady:
	s_waitcnt vmcnt(8)
	v_lshlrev_b32_e32 v80, 16, v28
	v_and_b32_e32 v81, 0xffff0000, v28
	v_lshlrev_b32_e32 v82, 16, v32
	v_and_b32_e32 v83, 0xffff0000, v32
	v_lshlrev_b32_e32 v84, 16, v29
	v_and_b32_e32 v85, 0xffff0000, v29
	v_lshlrev_b32_e32 v86, 16, v33
	v_and_b32_e32 v87, 0xffff0000, v33
	v_mul_f32_e32 v80, v80, v82
	v_mul_f32_e32 v81, v81, v83
	v_mul_f32_e32 v84, v84, v86
	v_mul_f32_e32 v85, v85, v87
	v_cvt_pk_bf16_f32 v68, v80, v81
	v_cvt_pk_bf16_f32 v69, v84, v85
	v_lshlrev_b32_e32 v80, 16, v30
	v_and_b32_e32 v81, 0xffff0000, v30
	v_lshlrev_b32_e32 v82, 16, v34
	v_and_b32_e32 v83, 0xffff0000, v34
	v_lshlrev_b32_e32 v84, 16, v31
	v_and_b32_e32 v85, 0xffff0000, v31
	v_lshlrev_b32_e32 v86, 16, v35
	v_and_b32_e32 v87, 0xffff0000, v35
	v_mul_f32_e32 v80, v80, v82
	v_mul_f32_e32 v81, v81, v83
	v_mul_f32_e32 v84, v84, v86
	v_mul_f32_e32 v85, v85, v87
	v_cvt_pk_bf16_f32 v70, v80, v81
	v_cvt_pk_bf16_f32 v71, v84, v85
	v_lshlrev_b32_e32 v80, 16, v212
	v_and_b32_e32 v81, 0xffff0000, v212
	v_lshlrev_b32_e32 v82, 16, v216
	v_and_b32_e32 v83, 0xffff0000, v216
	v_lshlrev_b32_e32 v84, 16, v213
	v_and_b32_e32 v85, 0xffff0000, v213
	v_lshlrev_b32_e32 v86, 16, v217
	v_and_b32_e32 v87, 0xffff0000, v217
	v_mul_f32_e32 v80, v80, v82
	v_mul_f32_e32 v81, v81, v83
	v_mul_f32_e32 v84, v84, v86
	v_mul_f32_e32 v85, v85, v87
	v_cvt_pk_bf16_f32 v246, v80, v81
	v_cvt_pk_bf16_f32 v247, v84, v85
	v_lshlrev_b32_e32 v80, 16, v214
	v_and_b32_e32 v81, 0xffff0000, v214
	v_lshlrev_b32_e32 v82, 16, v218
	v_and_b32_e32 v83, 0xffff0000, v218
	v_lshlrev_b32_e32 v84, 16, v215
	v_and_b32_e32 v85, 0xffff0000, v215
	v_lshlrev_b32_e32 v86, 16, v219
	v_and_b32_e32 v87, 0xffff0000, v219
	v_mul_f32_e32 v80, v80, v82
	v_mul_f32_e32 v81, v81, v83
	v_mul_f32_e32 v84, v84, v86
	v_mul_f32_e32 v85, v85, v87
	v_cvt_pk_bf16_f32 v248, v80, v81
	v_cvt_pk_bf16_f32 v249, v84, v85
	ds_write_b128 v158, v[68:71] offset:32768
	ds_write_b128 v158, v[36:39] offset:41472
	ds_write_b128 v158, v[40:43] offset:50176
	ds_write_b128 v228, v[246:249] offset:32768
	ds_write_b128 v228, v[220:223] offset:41472
	ds_write_b128 v228, v[224:227] offset:50176
	ds_write_b16 v230, v40 offset:20736
	ds_write_b16_d16_hi v230, v40 offset:20816
	ds_write_b16 v230, v41 offset:20896
	ds_write_b16_d16_hi v230, v41 offset:20976
	ds_write_b16 v230, v42 offset:21056
	ds_write_b16_d16_hi v230, v42 offset:21136
	ds_write_b16 v230, v43 offset:21216
	ds_write_b16_d16_hi v230, v43 offset:21296
	ds_write_b16 v230, v36 offset:31104
	ds_write_b16_d16_hi v230, v36 offset:31184
	ds_write_b16 v230, v37 offset:31264
	ds_write_b16_d16_hi v230, v37 offset:31344
	ds_write_b16 v230, v38 offset:31424
	ds_write_b16_d16_hi v230, v38 offset:31504
	ds_write_b16 v230, v39 offset:31584
	ds_write_b16_d16_hi v230, v39 offset:31664
	ds_write_b16 v231, v224 offset:20736
	ds_write_b16_d16_hi v231, v224 offset:20816
	ds_write_b16 v231, v225 offset:20896
	ds_write_b16_d16_hi v231, v225 offset:20976
	ds_write_b16 v231, v226 offset:21056
	ds_write_b16_d16_hi v231, v226 offset:21136
	ds_write_b16 v231, v227 offset:21216
	ds_write_b16_d16_hi v231, v227 offset:21296
	ds_write_b16 v231, v220 offset:31104
	ds_write_b16_d16_hi v231, v220 offset:31184
	ds_write_b16 v231, v221 offset:31264
	ds_write_b16_d16_hi v231, v221 offset:31344
	ds_write_b16 v231, v222 offset:31424
	ds_write_b16_d16_hi v231, v222 offset:31504
	ds_write_b16 v231, v223 offset:31584
	ds_write_b16_d16_hi v231, v223 offset:31664
	s_and_saveexec_b64 s[14:15], s[2:3]
	ds_write_b128 v229, v[8:11] offset:58880
	s_or_b64 exec, exec, s[14:15]
	s_waitcnt lgkmcnt(0)
	s_barrier
	s_andn2_b64 vcc, exec, s[56:57]
	s_cbranch_vccnz .Lscanh_nopfb
	s_lshl_b32 s14, s76, 5
	s_addk_i32 s14, 0x60
	s_and_b64 vcc, exec, s[12:13]
	v_add_u32_e32 v0, s14, v113
	s_cbranch_vccnz .Lscanh_ib
	v_add_u32_e32 v1, s74, v113
	v_add_u32_e32 v1, 0x60, v1
	v_cmp_lt_i32_e32 vcc, s47, v1
	s_and_saveexec_b64 s[14:15], vcc
	s_xor_b64 s[14:15], exec, s[14:15]
	v_add_u32_e32 v0, s38, v156
	v_add_u32_e32 v0, 0x9bf, v0
	s_andn2_saveexec_b64 s[14:15], s[14:15]
	v_sub_u32_e32 v0, 0xff, v0
	s_or_b64 exec, exec, s[14:15]
